# attention loop: V staging write of the first half-step deferred past barrier B, its WAR barrier removed (3 barriers per 2 KV tiles); plus early buffer_inv in grid barriers
# baseline (speedup 1.0000x reference)
; #define SBAR() __builtin_amdgcn_sched_barrier(0)
; #define VMW() asm volatile("s_waitcnt vmcnt(0)" ::: "memory")
; #define SLOAD_H(Kp, Vp, k0) do { S.st_v0 = load8(VROW(Vp, k0, sr)); S.st_v1 = load8(VROW(Vp, k0, 32 + sr));              \
;                          S.st_k0 = load8(KROW(Kp, k0)); S.st_k1 = load8(KROW(Kp, k0) + 64); S.st_k2 = load8(KROW(Kp, k0) + 128); } while (0)
; #define SWRITE_HV(bf) do { *(bf16x8*)(V_lds + (bf) * SHM_V + vst0) = S.st_v0; *(bf16x8*)(V_lds + (bf) * SHM_V + vst1) = S.st_v1; } while (0)
; #define SWRITE_H(bf) do { SWRITE_HV(bf); SWRITE_HK(bf); } while (0)
; #define MASKT(P0_, P1_, t) do { const int kb_ = KBASE(t); if (kb_ + KVBLK - 1 > qlo || kb_ <= qlo + QBLK - 1 - W) mask_tile(P0_, P1_, qm - kb_, (unsigned)W); } while (0)
; __device__ __forceinline__ void partialSM(f32x16& p0, f32x16& p1, float& m_reg, float& mn, float& alpha) {
;     float pmax = p0[0]; for (int r = 1; r < 16; ++r) pmax = fmaxf(pmax, p0[r]); for (int r = 0; r < 16; ++r) pmax = fmaxf(pmax, p1[r]);
;     { auto rr = __builtin_amdgcn_permlane32_swap(__float_as_uint(pmax), __float_as_uint(pmax), false, false);
;       pmax = fmaxf(__uint_as_float(rr[0]), __uint_as_float(rr[1])); }
;     constexpr float C2 = 1.4426950408889634f * SCALE;
;     if (__builtin_expect(__all((pmax - m_reg) * SCALE <= THR), 1)) { mn = m_reg; alpha = 1.f; }
;     else { mn = fmaxf(m_reg, pmax); alpha = __builtin_amdgcn_exp2f((m_reg - mn) * C2); m_reg = mn; }
;     const float mnL = -mn * C2;
;     for (int r = 0; r < 16; ++r) p0[r] = fmaf(p0[r], C2, mnL); for (int r = 0; r < 16; ++r) p1[r] = fmaf(p1[r], C2, mnL);
;     for (int r = 0; r < 16; ++r) p0[r] = __builtin_amdgcn_exp2f(p0[r]);
; __device__ __forceinline__ void attn_block(const BlockRef& cur, const BlockRef& nxt, int skv, int W, char* lds, Seam& S) {
;     ...
;     constexpr int NQL = 12;
;     ...
;     f32x16 pA0, pA1, pB0, pB1; float mnA, mnB, alA, alB; bf16x8 pa0, pa1, pa2, pa3;
;     char* q_lds = lds + LDS_Q + (wid * NQL_ * 64 + lane) * 16;
; #pragma unroll
;     for (int d0 = 0; d0 < NQL_; ++d0) *(bf16x8*)(q_lds + d0 * 1024) = S.qt[d0];
;     SWRITE_HV(0); SBAR();
;     if (NT > 1) { SLOAD_H(Kh, Vh, KBASE(1)); }
;     SBAR(); qkt<0>(pA0, pA1, K_lds, r32, hi, S.qr, q_lds);
;     MASKT(pA0, pA1, 0); partialSM(pA0, pA1, m_reg, mnA, alA);
;     if (NT > 1) { VMW(); SWRITE_H(1); }
;     __syncthreads();
.LBB0_537:
	v_max_f32_e32 v64, v85, v85
	v_max_f32_e32 v65, v84, v84
	v_max_f32_e32 v64, v65, v64
	v_max3_f32 v64, v64, v86, v87
	v_max3_f32 v64, v64, v88, v89
	v_max3_f32 v64, v64, v90, v91
	v_max3_f32 v64, v64, v92, v93
	v_max3_f32 v64, v64, v94, v95
	v_max3_f32 v64, v64, v96, v97
	v_max3_f32 v64, v64, v98, v99
	v_max3_f32 v64, v64, v68, v69
	v_max3_f32 v64, v64, v70, v71
	v_max3_f32 v64, v64, v72, v73
	v_max3_f32 v64, v64, v74, v75
	v_max3_f32 v64, v64, v76, v77
	v_max3_f32 v64, v64, v78, v79
	v_max3_f32 v64, v64, v80, v81
	v_max3_f32 v64, v64, v82, v83
	v_mov_b32_e32 v65, v64
	s_nop 1
	v_permlane32_swap_b32_e32 v64, v65
	v_max_f32_e32 v65, v65, v65
	v_max_f32_e32 v64, v64, v64
	v_max_f32_e32 v64, v64, v65
	v_max_f32_e32 v66, v172, v172
	v_sub_f32_e32 v65, v64, v172
	v_max_f32_e32 v64, v66, v64
	v_sub_f32_e32 v66, v172, v64
	v_mul_f32_e32 v66, 0x3dd53b94, v66
	v_mul_f32_e32 v65, 0x3d93cd3a, v65
	v_exp_f32_e32 v66, v66
	v_cmp_ge_f32_e32 vcc, s57, v65
	s_cmp_eq_u64 vcc, exec
	s_cselect_b64 s[0:1], -1, 0
	s_waitcnt vmcnt(0)
	v_cndmask_b32_e64 v227, v66, 1.0, s[0:1]
	v_cmp_gt_f32_e32 vcc, 1.0, v227
	s_waitcnt vmcnt(2)
	ds_write_b128 v203, v[160:163] offset:32768
	s_waitcnt vmcnt(1)
	ds_write_b128 v203, v[164:167] offset:32896
	s_waitcnt vmcnt(0)
	ds_write_b128 v203, v[168:171] offset:33024
	s_cbranch_vccz .LBB0_541
	s_and_saveexec_b64 s[48:49], s[4:5]
	ds_write_b32 v205, v227 offset:128
	s_or_b64 exec, exec, s[48:49]
	s_waitcnt lgkmcnt(0)
	ds_read_b128 v[100:103], v204 offset:224
	ds_read_b128 v[104:107], v204 offset:192
	ds_read_b128 v[108:111], v204 offset:160
	ds_read_b128 v[112:115], v204 offset:128
	s_waitcnt lgkmcnt(3)
	v_pk_mul_f32 v[62:63], v[62:63], v[102:103]
	s_waitcnt lgkmcnt(2)
	v_pk_mul_f32 v[58:59], v[58:59], v[106:107]
	s_waitcnt lgkmcnt(1)
	v_pk_mul_f32 v[54:55], v[54:55], v[110:111]
	s_waitcnt lgkmcnt(0)
	v_pk_mul_f32 v[50:51], v[50:51], v[114:115]
	v_pk_mul_f32 v[60:61], v[60:61], v[100:101]
	v_pk_mul_f32 v[56:57], v[56:57], v[104:105]
	v_pk_mul_f32 v[52:53], v[52:53], v[108:109]
	v_pk_mul_f32 v[48:49], v[48:49], v[112:113]
	v_pk_mul_f32 v[46:47], v[46:47], v[102:103]
	v_pk_mul_f32 v[42:43], v[42:43], v[106:107]
	v_pk_mul_f32 v[38:39], v[38:39], v[110:111]
	v_pk_mul_f32 v[34:35], v[34:35], v[114:115]
	v_pk_mul_f32 v[44:45], v[44:45], v[100:101]
	v_pk_mul_f32 v[40:41], v[40:41], v[104:105]
	v_pk_mul_f32 v[36:37], v[36:37], v[108:109]
	v_pk_mul_f32 v[32:33], v[32:33], v[112:113]
	v_pk_mul_f32 v[30:31], v[30:31], v[102:103]
	v_pk_mul_f32 v[26:27], v[26:27], v[106:107]
	v_pk_mul_f32 v[22:23], v[22:23], v[110:111]
	v_pk_mul_f32 v[18:19], v[18:19], v[114:115]
	v_pk_mul_f32 v[28:29], v[28:29], v[100:101]
	v_pk_mul_f32 v[24:25], v[24:25], v[104:105]
	v_pk_mul_f32 v[20:21], v[20:21], v[108:109]
	v_pk_mul_f32 v[16:17], v[16:17], v[112:113]
	v_pk_mul_f32 v[14:15], v[14:15], v[102:103]
	v_pk_mul_f32 v[10:11], v[10:11], v[106:107]
	v_pk_mul_f32 v[6:7], v[6:7], v[110:111]
	v_pk_mul_f32 v[2:3], v[2:3], v[114:115]
	v_pk_mul_f32 v[12:13], v[12:13], v[100:101]
	v_pk_mul_f32 v[8:9], v[8:9], v[104:105]
	v_pk_mul_f32 v[4:5], v[4:5], v[108:109]
	v_pk_mul_f32 v[0:1], v[0:1], v[112:113]
.LBB0_541:
	v_cndmask_b32_e64 v228, v64, v172, s[0:1]
	v_mul_f32_e32 v172, 0xbdd53b94, v228
	v_fmamk_f32 v64, v84, 0x3dd53b94, v172
	v_fmamk_f32 v65, v85, 0x3dd53b94, v172
	v_fmamk_f32 v66, v86, 0x3dd53b94, v172
	v_fmamk_f32 v67, v87, 0x3dd53b94, v172
	v_fmamk_f32 v100, v88, 0x3dd53b94, v172
	v_fmamk_f32 v101, v89, 0x3dd53b94, v172
	v_fmamk_f32 v102, v90, 0x3dd53b94, v172
	v_fmamk_f32 v103, v91, 0x3dd53b94, v172
	v_fmamk_f32 v104, v92, 0x3dd53b94, v172
	v_fmamk_f32 v105, v93, 0x3dd53b94, v172
	v_fmamk_f32 v106, v94, 0x3dd53b94, v172
	v_fmamk_f32 v107, v95, 0x3dd53b94, v172
	v_fmamk_f32 v96, v96, 0x3dd53b94, v172
	v_fmamk_f32 v97, v97, 0x3dd53b94, v172
	v_fmamk_f32 v98, v98, 0x3dd53b94, v172
	v_fmamk_f32 v99, v99, 0x3dd53b94, v172
	v_fmamk_f32 v84, v68, 0x3dd53b94, v172
	v_fmamk_f32 v93, v69, 0x3dd53b94, v172
	v_fmamk_f32 v94, v70, 0x3dd53b94, v172
	v_fmamk_f32 v95, v71, 0x3dd53b94, v172
	v_fmamk_f32 v173, v72, 0x3dd53b94, v172
	v_fmamk_f32 v85, v73, 0x3dd53b94, v172
	v_fmamk_f32 v86, v74, 0x3dd53b94, v172
	v_fmamk_f32 v87, v75, 0x3dd53b94, v172
	v_fmamk_f32 v88, v76, 0x3dd53b94, v172
	v_fmamk_f32 v89, v77, 0x3dd53b94, v172
	v_fmamk_f32 v90, v78, 0x3dd53b94, v172
	v_fmamk_f32 v91, v79, 0x3dd53b94, v172
	v_exp_f32_e32 v64, v64
	v_exp_f32_e32 v65, v65
	v_exp_f32_e32 v66, v66
	v_exp_f32_e32 v67, v67
	v_exp_f32_e32 v68, v100
	v_exp_f32_e32 v69, v101
	v_exp_f32_e32 v70, v102
	v_exp_f32_e32 v71, v103
	v_exp_f32_e32 v72, v104
	v_exp_f32_e32 v73, v105
	v_exp_f32_e32 v74, v106
	v_exp_f32_e32 v75, v107
	v_exp_f32_e32 v76, v96
	v_exp_f32_e32 v77, v97
	v_exp_f32_e32 v78, v98
	v_exp_f32_e32 v79, v99
	v_fmamk_f32 v92, v80, 0x3dd53b94, v172
	v_fmamk_f32 v174, v81, 0x3dd53b94, v172
	v_fmamk_f32 v175, v82, 0x3dd53b94, v172
	v_fmac_f32_e32 v172, 0x3dd53b94, v83
	s_waitcnt lgkmcnt(0)
	s_barrier
; __device__ __forceinline__ void finishSM(f32x16& p0, f32x16& p1, float alpha, float& l_reg, bf16x8& pa0, bf16x8& pa1, bf16x8& pa2, bf16x8& pa3) {
;     for (int r = 0; r < 16; ++r) p1[r] = __builtin_amdgcn_exp2f(p1[r]);
;     float ps = 0; for (int r = 0; r < 16; ++r) ps += p0[r]; for (int r = 0; r < 16; ++r) ps += p1[r];
;     { auto rr = __builtin_amdgcn_permlane32_swap(__float_as_uint(ps), __float_as_uint(ps), false, false);
;       ps = __uint_as_float(rr[0]) + __uint_as_float(rr[1]); }
;     l_reg = l_reg * alpha + ps;
;     ...
;     PK4(p0, 0, pa0); PK4(p0, 8, pa1); PK4(p1, 0, pa2); PK4(p1, 8, pa3);
; template <int KB>
; __device__ __forceinline__ void qkt(f32x16& p0, f32x16& p1, const char* K_lds, int r32, int hi, const bf16x8* qr, const char* q_lds) {
;     p0 = f32x16{}; p1 = f32x16{};
;     const char* kb[4];
; #pragma unroll
;     for (int dd = 0; dd < 4; ++dd) kb[dd] = K_lds + KB * SHM_K + KSWZ(r32, (dd * 16 + hi * 8) * 2);
; #pragma unroll
;     for (int d0 = 0; d0 < 12; ++d0) { const char* a = kb[d0 & 3] + (d0 >> 2) * 128;
;         bf16x8 b0 = *reinterpret_cast<const bf16x8*>(a);
;         bf16x8 b1 = *reinterpret_cast<const bf16x8*>(a + 32 * 384);
;         const bf16x8 qf = d0 < NQR ? qr[d0 < NQR ? d0 : 0] : *reinterpret_cast<const bf16x8*>(q_lds + (d0 - NQR) * 1024);
;         p0 = __builtin_amdgcn_mfma_f32_32x32x16_bf16(b0, qf, p0, 0, 0, 0);
;         p1 = __builtin_amdgcn_mfma_f32_32x32x16_bf16(b1, qf, p1, 0, 0, 0); }
	ds_write_b128 v218, v[152:155]
	ds_write_b128 v219, v[156:159]
	ds_read_b128 v[80:83], v212 offset:32768
	ds_read_b128 v[96:99], v212 offset:45056
	v_exp_f32_e32 v85, v85
	v_exp_f32_e32 v86, v86
	v_exp_f32_e32 v87, v87
	s_waitcnt lgkmcnt(1)
	v_mfma_f32_32x32x16_bf16 v[112:127], v[80:83], v[148:151], 0
	ds_read_b128 v[80:83], v213 offset:32768
	ds_read_b128 v[176:179], v213 offset:45056
	v_exp_f32_e32 v88, v88
	v_exp_f32_e32 v89, v89
	v_exp_f32_e32 v90, v90
	v_exp_f32_e32 v91, v91
	v_exp_f32_e32 v92, v92
	s_waitcnt lgkmcnt(2)
	v_mfma_f32_32x32x16_bf16 v[96:111], v[96:99], v[148:151], 0
	s_waitcnt lgkmcnt(1)
	v_mfma_f32_32x32x16_bf16 v[112:127], v[80:83], v[144:147], v[112:127]
	s_waitcnt lgkmcnt(0)
	v_mfma_f32_32x32x16_bf16 v[96:111], v[176:179], v[144:147], v[96:111]
	ds_read_b128 v[80:83], v215 offset:32768
	ds_read_b128 v[176:179], v215 offset:45056
	s_waitcnt lgkmcnt(1)
	v_mfma_f32_32x32x16_bf16 v[112:127], v[80:83], v[140:143], v[112:127]
	s_waitcnt lgkmcnt(0)
	v_mfma_f32_32x32x16_bf16 v[96:111], v[176:179], v[140:143], v[96:111]
	ds_read_b128 v[80:83], v214 offset:32768
	ds_read_b128 v[176:179], v214 offset:45056
	s_waitcnt lgkmcnt(1)
	v_mfma_f32_32x32x16_bf16 v[112:127], v[80:83], v[136:139], v[112:127]
	s_waitcnt lgkmcnt(0)
	v_mfma_f32_32x32x16_bf16 v[96:111], v[176:179], v[136:139], v[96:111]
	ds_read_b128 v[80:83], v212 offset:32896
	ds_read_b128 v[176:179], v212 offset:45184
	s_waitcnt lgkmcnt(1)
	v_mfma_f32_32x32x16_bf16 v[112:127], v[80:83], v[132:135], v[112:127]
	s_waitcnt lgkmcnt(0)
	v_mfma_f32_32x32x16_bf16 v[96:111], v[176:179], v[132:135], v[96:111]
	ds_read_b128 v[80:83], v213 offset:32896
	ds_read_b128 v[176:179], v213 offset:45184
	s_waitcnt lgkmcnt(1)
	v_mfma_f32_32x32x16_bf16 v[112:127], v[80:83], v[128:131], v[112:127]
	s_waitcnt lgkmcnt(0)
	v_mfma_f32_32x32x16_bf16 v[96:111], v[176:179], v[128:131], v[96:111]
	ds_read_b128 v[80:83], v215 offset:32896
	ds_read_b128 v[176:179], v215 offset:45184
	ds_read_b128 v[180:183], v211
	s_waitcnt lgkmcnt(0)
	v_mfma_f32_32x32x16_bf16 v[112:127], v[80:83], v[180:183], v[112:127]
	v_mfma_f32_32x32x16_bf16 v[96:111], v[176:179], v[180:183], v[96:111]
	ds_read_b128 v[80:83], v214 offset:32896
	ds_read_b128 v[176:179], v214 offset:45184
	ds_read_b128 v[180:183], v211 offset:1024
	s_waitcnt lgkmcnt(0)
	v_mfma_f32_32x32x16_bf16 v[112:127], v[80:83], v[180:183], v[112:127]
	v_mfma_f32_32x32x16_bf16 v[96:111], v[176:179], v[180:183], v[96:111]
	ds_read_b128 v[80:83], v212 offset:33024
	ds_read_b128 v[176:179], v212 offset:45312
	ds_read_b128 v[180:183], v211 offset:2048
	s_waitcnt lgkmcnt(0)
	v_mfma_f32_32x32x16_bf16 v[112:127], v[80:83], v[180:183], v[112:127]
	v_mfma_f32_32x32x16_bf16 v[96:111], v[176:179], v[180:183], v[96:111]
	ds_read_b128 v[80:83], v213 offset:33024
	ds_read_b128 v[176:179], v213 offset:45312
	ds_read_b128 v[180:183], v211 offset:3072
	s_waitcnt lgkmcnt(0)
	v_mfma_f32_32x32x16_bf16 v[112:127], v[80:83], v[180:183], v[112:127]
	v_mfma_f32_32x32x16_bf16 v[96:111], v[176:179], v[180:183], v[96:111]
	ds_read_b128 v[80:83], v215 offset:33024
	ds_read_b128 v[176:179], v215 offset:45312
	ds_read_b128 v[180:183], v211 offset:4096
	s_waitcnt lgkmcnt(0)
	v_mfma_f32_32x32x16_bf16 v[112:127], v[80:83], v[180:183], v[112:127]
	v_mfma_f32_32x32x16_bf16 v[96:111], v[176:179], v[180:183], v[96:111]
	ds_read_b128 v[80:83], v214 offset:33024
	ds_read_b128 v[176:179], v214 offset:45312
	ds_read_b128 v[180:183], v211 offset:5120
	s_waitcnt lgkmcnt(0)
	v_mfma_f32_32x32x16_bf16 v[112:127], v[80:83], v[180:183], v[112:127]
	v_exp_f32_e32 v83, v95
	v_exp_f32_e32 v95, v172
	v_add_f32_e32 v172, 0, v64
	v_add_f32_e32 v172, v65, v172
	v_add_f32_e32 v172, v66, v172
	v_add_f32_e32 v172, v67, v172
	v_add_f32_e32 v172, v68, v172
	v_add_f32_e32 v172, v69, v172
	v_add_f32_e32 v172, v70, v172
	v_add_f32_e32 v172, v71, v172
	v_add_f32_e32 v172, v72, v172
	v_add_f32_e32 v172, v73, v172
	v_add_f32_e32 v172, v74, v172
	v_add_f32_e32 v172, v75, v172
	v_exp_f32_e32 v80, v84
	v_add_f32_e32 v172, v76, v172
	v_exp_f32_e32 v81, v93
	v_add_f32_e32 v172, v77, v172
	v_exp_f32_e32 v82, v94
	v_add_f32_e32 v172, v78, v172
	v_add_f32_e32 v172, v79, v172
	v_exp_f32_e32 v84, v173
	v_add_f32_e32 v172, v80, v172
	v_add_f32_e32 v172, v81, v172
	v_add_f32_e32 v172, v82, v172
	v_add_f32_e32 v172, v83, v172
	v_add_f32_e32 v172, v84, v172
	v_add_f32_e32 v172, v85, v172
	v_add_f32_e32 v172, v86, v172
	v_add_f32_e32 v172, v87, v172
	v_add_f32_e32 v172, v88, v172
	v_exp_f32_e32 v93, v174
	v_add_f32_e32 v172, v89, v172
	v_mfma_f32_32x32x16_bf16 v[96:111], v[176:179], v[180:183], v[96:111]
	v_exp_f32_e32 v94, v175
	v_add_f32_e32 v172, v90, v172
	v_add_f32_e32 v172, v91, v172
	v_add_f32_e32 v172, v92, v172
	v_add_f32_e32 v172, v93, v172
	v_add_f32_e32 v172, v94, v172
	v_add_f32_e32 v231, v95, v172
	v_mov_b32_e32 v232, v231
	v_cvt_pk_bf16_f32 v172, v64, v65
	v_cvt_pk_bf16_f32 v173, v66, v67
	v_cvt_pk_bf16_f32 v174, v68, v69
	v_cvt_pk_bf16_f32 v175, v70, v71
	v_cvt_pk_bf16_f32 v176, v72, v73
	v_cvt_pk_bf16_f32 v177, v74, v75
	v_cvt_pk_bf16_f32 v178, v76, v77
	v_cvt_pk_bf16_f32 v179, v78, v79
	v_cvt_pk_bf16_f32 v180, v80, v81
	v_cvt_pk_bf16_f32 v181, v82, v83
	v_cvt_pk_bf16_f32 v182, v84, v85
	v_cvt_pk_bf16_f32 v183, v86, v87
	v_cvt_pk_bf16_f32 v184, v88, v89
	v_cvt_pk_bf16_f32 v185, v90, v91
	v_cvt_pk_bf16_f32 v186, v92, v93
	v_cvt_pk_bf16_f32 v187, v94, v95
	s_nop 1
	v_permlane32_swap_b32_e32 v231, v232
	v_permlane32_swap_b32_e32 v172, v174
	v_permlane32_swap_b32_e32 v173, v175
	v_permlane32_swap_b32_e32 v176, v178
	v_permlane32_swap_b32_e32 v177, v179
	v_permlane32_swap_b32_e32 v180, v182
	v_permlane32_swap_b32_e32 v181, v183
	v_permlane32_swap_b32_e32 v184, v186
	v_permlane32_swap_b32_e32 v185, v187
	s_add_i32 s0, s54, 1
	s_cmp_lt_i32 s0, s66
	s_cselect_b64 s[48:49], -1, 0
	s_cmp_ge_i32 s0, s66
	s_cbranch_scc1 .LBB0_543
	v_add_u32_e32 v152, 0x41, v229
	v_add_u32_e32 v154, 0x61, v229
	v_ashrrev_i32_e32 v153, 31, v152
	v_ashrrev_i32_e32 v155, 31, v154
	v_lshlrev_b64 v[152:153], 13, v[152:153]
	v_lshlrev_b64 v[154:155], 13, v[154:155]
	v_add_u32_e32 v160, 0x41, v230
	v_lshl_add_u64 v[152:153], v[194:195], 0, v[152:153]
	v_lshl_add_u64 v[156:157], v[194:195], 0, v[154:155]
	v_mad_i64_i32 v[168:169], s[0:1], v160, s9, v[196:197]
	global_load_dwordx4 v[152:155], v[152:153], off
	s_nop 0
	global_load_dwordx4 v[156:159], v[156:157], off
	s_nop 0
	global_load_dwordx4 v[160:163], v[168:169], off
	global_load_dwordx4 v[164:167], v[168:169], off offset:128
	s_nop 0
	global_load_dwordx4 v[168:171], v[168:169], off offset:256
